# grid barrier: acquire-side buffer_inv sc1 issued at arrival (overlapping the wait) instead of after the release is observed
# speedup vs baseline: 1.0048x; 1.0048x over previous
.LBB0_66:
	s_or_b64 exec, exec, s[8:9]
	v_cvt_f32_u32_e32 v4, v2
	s_waitcnt vmcnt(0)
	v_readfirstlane_b32 s6, v3
	v_sub_u32_e32 v3, 0, v2
	v_rcp_iflag_f32_e32 v4, v4
	v_add_u32_e32 v5, s6, v1
	v_mul_f32_e32 v4, 0x4f7ffffe, v4
	v_cvt_u32_f32_e32 v4, v4
	v_mul_lo_u32 v1, v3, v4
	v_mul_hi_u32 v1, v4, v1
	v_add_u32_e32 v1, v4, v1
	v_mul_hi_u32 v1, v5, v1
	v_mul_lo_u32 v3, v1, v2
	v_sub_u32_e32 v3, v5, v3
	v_add_u32_e32 v4, 1, v1
	v_cmp_ge_u32_e32 vcc, v3, v2
	s_nop 1
	v_cndmask_b32_e32 v1, v1, v4, vcc
	v_sub_u32_e32 v4, v3, v2
	v_cndmask_b32_e32 v3, v3, v4, vcc
	v_add_u32_e32 v4, 1, v1
	v_cmp_ge_u32_e32 vcc, v3, v2
	v_add_u32_e32 v3, 1, v5
	s_nop 0
	v_cndmask_b32_e32 v1, v1, v4, vcc
	v_mul_lo_u32 v4, v2, v1
	v_add_u32_e32 v2, v4, v2
	v_cmp_ne_u32_e32 vcc, v3, v2
	s_and_saveexec_b64 s[6:7], vcc
	s_xor_b64 s[6:7], exec, s[6:7]
	s_cbranch_execz .LBB0_80
	s_waitcnt lgkmcnt(0)
	v_mov_b32_e32 v0, 0x2000
	buffer_inv sc1
	s_add_u32 s12, s96, 0x3500
	s_addc_u32 s13, s97, 0
	v_mov_b32_e32 v0, 0
	global_load_dword v0, v0, s[12:13] sc1
	s_waitcnt vmcnt(0)
	v_cmp_eq_u32_e32 vcc, v0, v1
	s_and_saveexec_b64 s[8:9], vcc
	s_cbranch_execz .LBB0_79
	s_add_u32 s10, s40, 0x4200
	s_addc_u32 s11, s41, 0
	s_mov_b32 s24, 1
	s_mov_b64 s[14:15], 0
	v_mov_b32_e32 v0, 0
	s_branch .LBB0_70

.LBB0_79:
	s_or_b64 exec, exec, s[8:9]
	s_waitcnt vmcnt(0)
	s_waitcnt vmcnt(0)
.LBB0_80:
	s_andn2_saveexec_b64 s[6:7], s[6:7]
	s_cbranch_execz .LBB0_100
	s_mov_b64 s[6:7], exec
	buffer_wbl2 sc1
	buffer_inv sc1
	s_waitcnt lgkmcnt(0)
	s_waitcnt vmcnt(0)
	v_mbcnt_lo_u32_b32 v1, s6, 0
	v_mbcnt_hi_u32_b32 v1, s7, v1
	v_cmp_eq_u32_e32 vcc, 0, v1
	s_and_saveexec_b64 s[8:9], vcc
	s_cbranch_execz .LBB0_83
	s_bcnt1_i32_b64 s6, s[6:7]
	v_mov_b32_e32 v2, 0x7000
	v_mov_b32_e32 v3, s6
	global_atomic_add v2, v2, v3, s[40:41] offset:1024 sc0

.LBB0_97:
	s_or_b64 exec, exec, s[6:7]
	s_mov_b64 s[6:7], exec
	v_mbcnt_lo_u32_b32 v0, s6, 0
	v_mbcnt_hi_u32_b32 v0, s7, v0
	v_cmp_eq_u32_e32 vcc, 0, v0
	s_waitcnt vmcnt(0)
	s_and_saveexec_b64 s[8:9], vcc
	s_cbranch_execz .LBB0_99
	s_bcnt1_i32_b64 s6, s[6:7]
	v_mov_b32_e32 v0, 0x2000
	v_mov_b32_e32 v1, s6
	global_atomic_add v0, v1, s[4:5] offset:1024

.LBB0_181:
	s_or_b64 exec, exec, s[8:9]
	v_cvt_f32_u32_e32 v5, v3
	s_waitcnt vmcnt(0)
	v_readfirstlane_b32 s0, v4
	v_sub_u32_e32 v4, 0, v3
	v_rcp_iflag_f32_e32 v5, v5
	v_add_u32_e32 v6, s0, v0
	v_mul_f32_e32 v5, 0x4f7ffffe, v5
	v_cvt_u32_f32_e32 v5, v5
	v_mul_lo_u32 v0, v4, v5
	v_mul_hi_u32 v0, v5, v0
	v_add_u32_e32 v0, v5, v0
	v_mul_hi_u32 v0, v6, v0
	v_mul_lo_u32 v4, v0, v3
	v_sub_u32_e32 v4, v6, v4
	v_add_u32_e32 v5, 1, v0
	v_cmp_ge_u32_e32 vcc, v4, v3
	s_nop 1
	v_cndmask_b32_e32 v0, v0, v5, vcc
	v_sub_u32_e32 v5, v4, v3
	v_cndmask_b32_e32 v4, v4, v5, vcc
	v_add_u32_e32 v5, 1, v0
	v_cmp_ge_u32_e32 vcc, v4, v3
	v_add_u32_e32 v4, 1, v6
	s_nop 0
	v_cndmask_b32_e32 v0, v0, v5, vcc
	v_mul_lo_u32 v5, v3, v0
	v_add_u32_e32 v3, v5, v3
	v_cmp_ne_u32_e32 vcc, v4, v3
	s_and_saveexec_b64 s[0:1], vcc
	s_xor_b64 s[8:9], exec, s[0:1]
	s_cbranch_execz .LBB0_195
	s_waitcnt lgkmcnt(0)
	buffer_inv sc1
	s_add_u32 s0, s96, 0x3500
	s_addc_u32 s1, s97, 0
	global_load_dword v2, v1, s[0:1] sc1
	s_waitcnt vmcnt(0)
	v_cmp_eq_u32_e32 vcc, v2, v0
	s_and_saveexec_b64 s[10:11], vcc
	s_cbranch_execz .LBB0_194
	s_mov_b32 s19, 1
	s_mov_b64 s[12:13], 0
	s_branch .LBB0_185

.LBB0_194:
	s_or_b64 exec, exec, s[10:11]
	s_waitcnt vmcnt(0)
	s_waitcnt vmcnt(0)
.LBB0_195:
	s_andn2_saveexec_b64 s[0:1], s[8:9]
	s_cbranch_execz .LBB0_215
	s_mov_b64 s[0:1], exec
	buffer_wbl2 sc1
	buffer_inv sc1
	s_waitcnt lgkmcnt(0)
	s_waitcnt vmcnt(0)
	v_mbcnt_lo_u32_b32 v0, s0, 0
	v_mbcnt_hi_u32_b32 v0, s1, v0
	v_cmp_eq_u32_e32 vcc, 0, v0
	s_and_saveexec_b64 s[8:9], vcc
	s_cbranch_execz .LBB0_198
	s_bcnt1_i32_b64 s0, s[0:1]
	v_mov_b32_e32 v3, s0
	v_readlane_b32 s0, v252, 48
	v_readlane_b32 s1, v252, 49
	s_nop 4
	global_atomic_add v3, v1, v3, s[0:1] sc0

.LBB0_212:
	s_or_b64 exec, exec, s[8:9]
	s_mov_b64 s[0:1], exec
	v_mbcnt_lo_u32_b32 v0, s0, 0
	v_mbcnt_hi_u32_b32 v0, s1, v0
	v_cmp_eq_u32_e32 vcc, 0, v0
	s_waitcnt vmcnt(0)
	s_and_saveexec_b64 s[8:9], vcc
	s_cbranch_execz .LBB0_214
	s_bcnt1_i32_b64 s0, s[0:1]
	v_mov_b32_e32 v0, s0
	global_atomic_add v205, v0, s[6:7] offset:1024

.LBB0_859:
	s_or_b64 exec, exec, s[8:9]
	v_cvt_f32_u32_e32 v5, v3
	s_waitcnt vmcnt(0)
	v_readfirstlane_b32 s0, v4
	v_sub_u32_e32 v4, 0, v3
	v_rcp_iflag_f32_e32 v5, v5
	v_add_u32_e32 v6, s0, v0
	v_mul_f32_e32 v5, 0x4f7ffffe, v5
	v_cvt_u32_f32_e32 v5, v5
	v_mul_lo_u32 v0, v4, v5
	v_mul_hi_u32 v0, v5, v0
	v_add_u32_e32 v0, v5, v0
	v_mul_hi_u32 v0, v6, v0
	v_mul_lo_u32 v4, v0, v3
	v_sub_u32_e32 v4, v6, v4
	v_add_u32_e32 v5, 1, v0
	v_cmp_ge_u32_e32 vcc, v4, v3
	s_nop 1
	v_cndmask_b32_e32 v0, v0, v5, vcc
	v_sub_u32_e32 v5, v4, v3
	v_cndmask_b32_e32 v4, v4, v5, vcc
	v_add_u32_e32 v5, 1, v0
	v_cmp_ge_u32_e32 vcc, v4, v3
	v_add_u32_e32 v4, 1, v6
	s_nop 0
	v_cndmask_b32_e32 v0, v0, v5, vcc
	v_mul_lo_u32 v5, v3, v0
	v_add_u32_e32 v3, v5, v3
	v_cmp_ne_u32_e32 vcc, v4, v3
	s_and_saveexec_b64 s[0:1], vcc
	s_xor_b64 s[8:9], exec, s[0:1]
	s_cbranch_execz .LBB0_873
	s_waitcnt lgkmcnt(0)
	buffer_inv sc1
	s_add_u32 s0, s96, 0x3500
	s_addc_u32 s1, s97, 0
	global_load_dword v2, v1, s[0:1] sc1
	s_waitcnt vmcnt(0)
	v_cmp_eq_u32_e32 vcc, v2, v0
	s_and_saveexec_b64 s[10:11], vcc
	s_cbranch_execz .LBB0_872
	s_mov_b32 s26, 1
	s_mov_b64 s[12:13], 0
	s_branch .LBB0_863

.LBB0_890:
	s_or_b64 exec, exec, s[8:9]
	s_mov_b64 s[0:1], exec
	v_mbcnt_lo_u32_b32 v0, s0, 0
	v_mbcnt_hi_u32_b32 v0, s1, v0
	v_cmp_eq_u32_e32 vcc, 0, v0
	s_waitcnt vmcnt(0)
	s_and_saveexec_b64 s[8:9], vcc
	s_cbranch_execz .LBB0_128
	s_bcnt1_i32_b64 s0, s[0:1]
	v_mov_b32_e32 v0, s0
	global_atomic_add v205, v0, s[6:7] offset:1024
	s_branch .LBB0_128
